# P1 epilogue: rotary (cos, sin) rows of the wave's eight steps touched once up front so the per-step loads hit the CU cache
# baseline (speedup 1.0000x reference)
.LBB0_105:
	s_cmp_lt_i32 s18, 4
	s_cselect_b64 s[0:1], -1, 0
	s_and_b64 s[0:1], s[28:29], s[0:1]
	v_lshl_add_u32 v206, s6, 8, v147
	v_cndmask_b32_e64 v128, 0, 1, s[0:1]
	v_cmp_ne_u32_e64 s[6:7], 1, v128
	s_andn2_b64 vcc, exec, s[0:1]
	v_cmp_gt_i32_e64 s[8:9], s53, v206
	v_readlane_b32 s33, v254, 0
	s_cbranch_vccnz .LBB0_107
	v_cndmask_b32_e64 v128, v184, v185, s[8:9]
	v_and_b32_e32 v128, v128, v206
	v_lshlrev_b32_e32 v128, 6, v128
	v_and_b32_e32 v214, 15, v145
	v_lshlrev_b32_e32 v214, 6, v214
	v_sub_u32_e32 v214, v128, v214
	v_and_b32_e32 v215, 63, v145
	v_lshl_add_u32 v214, v215, 4, v214
	v_add_u32_e32 v215, 0x2000, v214
	global_load_dwordx4 v[216:219], v214, s[16:17]
	global_load_dwordx4 v[220:223], v214, s[16:17] offset:1024
	global_load_dwordx4 v[224:227], v214, s[16:17] offset:2048
	global_load_dwordx4 v[228:231], v214, s[16:17] offset:3072
	global_load_dwordx4 v[232:235], v215, s[16:17]
	global_load_dwordx4 v[236:239], v215, s[16:17] offset:1024
	global_load_dwordx4 v[240:243], v215, s[16:17] offset:2048
	global_load_dwordx4 v[244:247], v215, s[16:17] offset:3072
	global_load_dwordx4 v[136:139], v128, s[16:17]
	global_load_dwordx4 v[140:143], v128, s[16:17] offset:16
	global_load_dwordx4 v[132:135], v128, s[16:17] offset:32
	s_nop 0
	global_load_dwordx4 v[128:131], v128, s[16:17] offset:48
	s_branch .LBB0_108
